# attention steady loop: row-max tree and rescale decision moved from the serial section into the first P.V MFMA gaps; exps follow in the remaining gaps
# speedup vs baseline: 1.0089x; 1.0053x over previous
.LBB0_310:
	s_lshl_b32 s14, s14, 1
	v_add_u32_e32 v217, s14, v244
	ds_read_b64_tr_b16 v[208:209], v217 offset:24576
	ds_read_b64_tr_b16 v[210:211], v217 offset:25088
	v_mfma_f32_32x32x16_bf16 v[128:143], v[204:207], v[172:175], v[64:79]
	v_add_f32_e32 v112, v96, v97
	v_add_f32_e32 v112, v98, v112
	v_add_f32_e32 v112, v99, v112
	v_add_f32_e32 v112, v100, v112
	v_add_f32_e32 v112, v101, v112
	v_cvt_pk_bf16_f32 v164, v96, v97
	v_cvt_pk_bf16_f32 v165, v98, v99
	ds_read_b64_tr_b16 v[96:97], v217 offset:28672
	ds_read_b64_tr_b16 v[98:99], v217 offset:29184
	v_add_f32_e32 v112, v102, v112
	v_add_f32_e32 v112, v103, v112
	v_add_f32_e32 v112, v104, v112
	v_add_f32_e32 v144, v105, v112
	v_mfma_f32_32x32x16_bf16 v[112:127], v[200:203], v[172:175], v[64:79]
	v_cvt_pk_bf16_f32 v166, v100, v101
	v_cvt_pk_bf16_f32 v167, v102, v103
	ds_read_b64_tr_b16 v[100:101], v217 offset:25600
	ds_read_b64_tr_b16 v[102:103], v217 offset:26112
	v_mfma_f32_32x32x16_bf16 v[128:143], v[196:199], v[168:171], v[128:143]
	v_add_f32_e32 v144, v106, v144
	v_add_f32_e32 v144, v107, v144
	v_add_f32_e32 v144, v108, v144
	v_add_f32_e32 v144, v109, v144
	v_cvt_pk_bf16_f32 v156, v104, v105
	v_cvt_pk_bf16_f32 v157, v106, v107
	ds_read_b64_tr_b16 v[104:105], v217 offset:29696
	ds_read_b64_tr_b16 v[106:107], v217 offset:30208
	v_mfma_f32_32x32x16_bf16 v[112:127], v[192:195], v[168:171], v[112:127]
	v_add_f32_e32 v144, v110, v144
	v_add_f32_e32 v144, v111, v144
	v_add_f32_e32 v144, v80, v144
	v_add_f32_e32 v144, v81, v144
	v_cvt_pk_bf16_f32 v158, v108, v109
	v_cvt_pk_bf16_f32 v159, v110, v111
	ds_read_b64_tr_b16 v[108:109], v217 offset:26624
	ds_read_b64_tr_b16 v[110:111], v217 offset:27136
	v_mfma_f32_32x32x16_bf16 v[128:143], v[188:191], v[160:163], v[128:143]
	v_add_f32_e32 v144, v82, v144
	v_add_f32_e32 v144, v83, v144
	v_add_f32_e32 v144, v84, v144
	v_add_f32_e32 v144, v85, v144
	v_cvt_pk_bf16_f32 v148, v80, v81
	v_cvt_pk_bf16_f32 v149, v82, v83
	ds_read_b64_tr_b16 v[80:81], v217 offset:30720
	ds_read_b64_tr_b16 v[82:83], v217 offset:31232
	v_mfma_f32_32x32x16_bf16 v[112:127], v[184:187], v[160:163], v[112:127]
	v_add_f32_e32 v144, v86, v144
	v_add_f32_e32 v144, v87, v144
	v_add_f32_e32 v144, v88, v144
	v_add_f32_e32 v144, v89, v144
	v_cvt_pk_bf16_f32 v150, v84, v85
	v_cvt_pk_bf16_f32 v151, v86, v87
	ds_read_b64_tr_b16 v[84:85], v217 offset:27648
	ds_read_b64_tr_b16 v[86:87], v217 offset:28160
	v_mfma_f32_32x32x16_bf16 v[128:143], v[180:183], v[152:155], v[128:143]
	v_add_f32_e32 v144, v90, v144
	v_add_f32_e32 v144, v91, v144
	v_add_f32_e32 v144, v92, v144
	v_add_f32_e32 v180, v93, v144
	v_cvt_pk_bf16_f32 v144, v88, v89
	v_cvt_pk_bf16_f32 v145, v90, v91
	ds_read_b64_tr_b16 v[88:89], v217 offset:31744
	ds_read_b64_tr_b16 v[90:91], v217 offset:32256
	v_mfma_f32_32x32x16_bf16 v[112:127], v[176:179], v[152:155], v[112:127]
	v_add_f32_e32 v146, v94, v180
	v_add_f32_e32 v176, v95, v146
	v_cvt_pk_bf16_f32 v146, v92, v93
	v_cvt_pk_bf16_f32 v147, v94, v95
	s_add_i32 m0, s24, s63
	s_mov_b32 s14, s32
	s_mov_b32 s15, s70
	global_load_lds_dwordx4 v212, s[14:15]
	s_lshl_b32 s14, s22, 1
	s_add_i32 s14, s14, s64
	s_mov_b32 m0, s14
	s_add_i32 s14, s14, 0x1f80
	global_load_lds_dwordx4 v226, s[98:99]
	s_mov_b32 m0, s14
	s_nop 0
	global_load_lds_dwordx4 v226, s[98:99] offset:128
	s_waitcnt lgkmcnt(12)
	v_mfma_f32_32x32x16_bf16 v[32:47], v[164:167], v[208:211], v[32:47]
	v_max_f32_e32 v222, v128, v129
	v_max3_f32 v223, v130, v131, v113
	v_max3_f32 v222, v222, v112, v114
	v_max3_f32 v222, v222, v115, v132
	ds_read_b64_tr_b16 v[92:93], v217 offset:32768
	ds_read_b64_tr_b16 v[94:95], v217 offset:33280
	v_mfma_f32_32x32x16_bf16 v[48:63], v[164:167], v[96:99], v[48:63]
	v_max3_f32 v223, v223, v134, v135
	v_max3_f32 v222, v222, v133, v116
	v_max3_f32 v223, v223, v118, v119
	v_max3_f32 v222, v222, v117, v136
	ds_read_b64_tr_b16 v[96:97], v217 offset:36864
	ds_read_b64_tr_b16 v[98:99], v217 offset:37376
	s_waitcnt lgkmcnt(12)
	v_mfma_f32_32x32x16_bf16 v[32:47], v[156:159], v[100:103], v[32:47]
	v_max3_f32 v223, v223, v138, v139
	v_max3_f32 v222, v222, v137, v120
	v_max3_f32 v223, v223, v122, v123
	v_max3_f32 v222, v222, v121, v140
	ds_read_b64_tr_b16 v[100:101], v217 offset:33792
	ds_read_b64_tr_b16 v[102:103], v217 offset:34304
	v_mfma_f32_32x32x16_bf16 v[48:63], v[156:159], v[104:107], v[48:63]
	v_max3_f32 v223, v223, v142, v143
	v_max3_f32 v222, v222, v141, v124
	v_max3_f32 v223, v223, v126, v127
	v_max3_f32 v222, v222, v125, v223
	ds_read_b64_tr_b16 v[104:105], v217 offset:37888
	ds_read_b64_tr_b16 v[106:107], v217 offset:38400
	s_waitcnt lgkmcnt(12)
	v_mfma_f32_32x32x16_bf16 v[32:47], v[148:151], v[108:111], v[32:47]
	v_mov_b32_e32 v223, v222
	v_add_f32_e32 v215, v249, v176
	s_nop 0
	v_permlane32_swap_b32_e32 v222, v223
	v_max_f32_e32 v222, v222, v223
	v_cmp_lt_f32_e32 vcc, s33, v222
	s_nop 0
	s_mov_b64 s[20:21], vcc
	s_cbranch_vccnz .LBB0_318
.LBB0_311:
	v_exp_f32_e32 v128, v128
	v_exp_f32_e32 v129, v129
	ds_read_b64_tr_b16 v[108:109], v217 offset:34816
	ds_read_b64_tr_b16 v[110:111], v217 offset:35328
	v_mfma_f32_32x32x16_bf16 v[48:63], v[148:151], v[80:83], v[48:63]
	v_exp_f32_e32 v130, v130
	v_exp_f32_e32 v131, v131
	v_exp_f32_e32 v132, v132
	ds_read_b64_tr_b16 v[188:189], v217 offset:38912
	ds_read_b64_tr_b16 v[190:191], v217 offset:39424
	s_waitcnt lgkmcnt(12)
	v_mfma_f32_32x32x16_bf16 v[32:47], v[144:147], v[84:87], v[32:47]
	v_exp_f32_e32 v133, v133
	v_exp_f32_e32 v134, v134
	v_exp_f32_e32 v135, v135
	ds_read_b64_tr_b16 v[84:85], v217 offset:35840
	ds_read_b64_tr_b16 v[86:87], v217 offset:36352
	v_mfma_f32_32x32x16_bf16 v[48:63], v[144:147], v[88:91], v[48:63]
	v_exp_f32_e32 v136, v136
	v_exp_f32_e32 v137, v137
	v_exp_f32_e32 v138, v138
	ds_read_b64_tr_b16 v[88:89], v217 offset:39936
	ds_read_b64_tr_b16 v[90:91], v217 offset:40448
	s_waitcnt lgkmcnt(12)
	v_mfma_f32_32x32x16_bf16 v[16:31], v[164:167], v[92:95], v[16:31]
	v_exp_f32_e32 v139, v139
	v_exp_f32_e32 v140, v140
	v_exp_f32_e32 v141, v141
	v_add_u32_e32 v92, s22, v247
	ds_read_b128 v[80:83], v92
	ds_read_b128 v[200:203], v92 offset:512
	v_mfma_f32_32x32x16_bf16 v[0:15], v[164:167], v[96:99], v[0:15]
	v_exp_f32_e32 v142, v142
	v_exp_f32_e32 v143, v143
	v_exp_f32_e32 v112, v112
	ds_read_b128 v[204:207], v92 offset:2048
	ds_read_b128 v[196:199], v92 offset:2560
	s_waitcnt lgkmcnt(12)
	v_mfma_f32_32x32x16_bf16 v[16:31], v[156:159], v[100:103], v[16:31]
	v_exp_f32_e32 v113, v113
	v_exp_f32_e32 v114, v114
	v_exp_f32_e32 v115, v115
	ds_read_b128 v[192:195], v92 offset:4096
	ds_read_b128 v[184:187], v92 offset:4608
	v_mfma_f32_32x32x16_bf16 v[0:15], v[156:159], v[104:107], v[0:15]
	v_exp_f32_e32 v116, v116
	v_exp_f32_e32 v117, v117
	v_exp_f32_e32 v118, v118
	ds_read_b128 v[180:183], v92 offset:6144
	ds_read_b128 v[176:179], v92 offset:6656
	s_waitcnt lgkmcnt(12)
	v_mfma_f32_32x32x16_bf16 v[16:31], v[148:151], v[108:111], v[16:31]
	v_exp_f32_e32 v119, v119
	v_exp_f32_e32 v120, v120
	v_exp_f32_e32 v121, v121
	v_mfma_f32_32x32x16_bf16 v[0:15], v[148:151], v[188:191], v[0:15]
	v_exp_f32_e32 v122, v122
	v_exp_f32_e32 v123, v123
	s_waitcnt lgkmcnt(8)
	v_mfma_f32_32x32x16_bf16 v[16:31], v[144:147], v[84:87], v[16:31]
	v_exp_f32_e32 v124, v124
	v_exp_f32_e32 v125, v125
	v_mfma_f32_32x32x16_bf16 v[0:15], v[144:147], v[88:91], v[0:15]
	v_exp_f32_e32 v126, v126
	v_exp_f32_e32 v127, v127
	s_waitcnt vmcnt(3) lgkmcnt(0)
	s_barrier
	s_cmp_eq_u64 s[20:21], 0
	s_cbranch_scc1 .LBB0_313
	s_waitcnt lgkmcnt(0)
	v_add_u32_e32 v208, s65, v248
	ds_read_b128 v[84:87], v208 offset:96
	ds_read_b128 v[88:91], v208 offset:64
	ds_read_b128 v[92:95], v208 offset:32
	ds_read_b128 v[96:99], v208
	s_waitcnt lgkmcnt(3)
	v_pk_mul_f32 v[44:45], v[44:45], v[84:85]
	s_waitcnt lgkmcnt(2)
	v_pk_mul_f32 v[40:41], v[40:41], v[88:89]
	s_waitcnt lgkmcnt(1)
	v_pk_mul_f32 v[36:37], v[36:37], v[92:93]
	v_pk_mul_f32 v[46:47], v[46:47], v[86:87]
	v_pk_mul_f32 v[42:43], v[42:43], v[90:91]
	v_pk_mul_f32 v[38:39], v[38:39], v[94:95]
	s_waitcnt lgkmcnt(0)
	v_pk_mul_f32 v[34:35], v[34:35], v[98:99]
	v_pk_mul_f32 v[32:33], v[32:33], v[96:97]
	v_pk_mul_f32 v[60:61], v[60:61], v[84:85]
	v_pk_mul_f32 v[56:57], v[56:57], v[88:89]
	v_pk_mul_f32 v[52:53], v[52:53], v[92:93]
	v_pk_mul_f32 v[62:63], v[62:63], v[86:87]
	v_pk_mul_f32 v[58:59], v[58:59], v[90:91]
	v_pk_mul_f32 v[54:55], v[54:55], v[94:95]
	v_pk_mul_f32 v[50:51], v[50:51], v[98:99]
	v_pk_mul_f32 v[48:49], v[48:49], v[96:97]
	v_pk_mul_f32 v[28:29], v[28:29], v[84:85]
	v_pk_mul_f32 v[24:25], v[24:25], v[88:89]
	v_pk_mul_f32 v[20:21], v[20:21], v[92:93]
	v_pk_mul_f32 v[30:31], v[30:31], v[86:87]
	v_pk_mul_f32 v[26:27], v[26:27], v[90:91]
	v_pk_mul_f32 v[22:23], v[22:23], v[94:95]
	v_pk_mul_f32 v[18:19], v[18:19], v[98:99]
	v_pk_mul_f32 v[16:17], v[16:17], v[96:97]
	v_pk_mul_f32 v[12:13], v[12:13], v[84:85]
	v_pk_mul_f32 v[8:9], v[8:9], v[88:89]
	v_pk_mul_f32 v[4:5], v[4:5], v[92:93]
	v_pk_mul_f32 v[14:15], v[14:15], v[86:87]
	v_pk_mul_f32 v[10:11], v[10:11], v[90:91]
	v_pk_mul_f32 v[6:7], v[6:7], v[94:95]
	v_pk_mul_f32 v[2:3], v[2:3], v[98:99]
	v_pk_mul_f32 v[0:1], v[0:1], v[96:97]
.LBB0_313:
	s_add_i32 s14, s22, 0x2000
	s_cmpk_lg_i32 s22, 0x4000
	s_cselect_b32 s66, s14, 0
	s_lshl_b32 s14, s24, 1
	v_add_u32_e32 v209, s14, v244
	ds_read_b64_tr_b16 v[188:189], v209 offset:24576
	ds_read_b64_tr_b16 v[190:191], v209 offset:25088
	v_mfma_f32_32x32x16_bf16 v[96:111], v[80:83], v[172:175], v[64:79]
	v_add_f32_e32 v84, v128, v129
	v_add_f32_e32 v84, v130, v84
	v_add_f32_e32 v84, v131, v84
	v_add_f32_e32 v84, v132, v84
	v_add_f32_e32 v84, v133, v84
	v_cvt_pk_bf16_f32 v164, v128, v129
	v_cvt_pk_bf16_f32 v165, v130, v131
	ds_read_b64_tr_b16 v[128:129], v209 offset:28672
	ds_read_b64_tr_b16 v[130:131], v209 offset:29184
	v_add_f32_e32 v80, v134, v84
	v_add_f32_e32 v80, v135, v80
	v_add_f32_e32 v80, v136, v80
	v_add_f32_e32 v144, v137, v80
	v_mfma_f32_32x32x16_bf16 v[80:95], v[200:203], v[172:175], v[64:79]
	v_cvt_pk_bf16_f32 v166, v132, v133
	v_cvt_pk_bf16_f32 v167, v134, v135
	ds_read_b64_tr_b16 v[132:133], v209 offset:25600
	ds_read_b64_tr_b16 v[134:135], v209 offset:26112
	v_mfma_f32_32x32x16_bf16 v[96:111], v[204:207], v[168:171], v[96:111]
	v_add_f32_e32 v144, v138, v144
	v_add_f32_e32 v144, v139, v144
	v_add_f32_e32 v144, v140, v144
	v_add_f32_e32 v144, v141, v144
	v_cvt_pk_bf16_f32 v156, v136, v137
	v_cvt_pk_bf16_f32 v157, v138, v139
	ds_read_b64_tr_b16 v[136:137], v209 offset:29696
	ds_read_b64_tr_b16 v[138:139], v209 offset:30208
	v_mfma_f32_32x32x16_bf16 v[80:95], v[196:199], v[168:171], v[80:95]
	v_add_f32_e32 v144, v142, v144
	v_add_f32_e32 v144, v143, v144
	v_add_f32_e32 v144, v112, v144
	v_add_f32_e32 v144, v113, v144
	v_cvt_pk_bf16_f32 v158, v140, v141
	v_cvt_pk_bf16_f32 v159, v142, v143
	ds_read_b64_tr_b16 v[140:141], v209 offset:26624
	ds_read_b64_tr_b16 v[142:143], v209 offset:27136
	v_mfma_f32_32x32x16_bf16 v[96:111], v[192:195], v[160:163], v[96:111]
	v_add_f32_e32 v144, v114, v144
	v_add_f32_e32 v144, v115, v144
	v_add_f32_e32 v144, v116, v144
	v_add_f32_e32 v144, v117, v144
	v_cvt_pk_bf16_f32 v148, v112, v113
	v_cvt_pk_bf16_f32 v149, v114, v115
	ds_read_b64_tr_b16 v[112:113], v209 offset:30720
	ds_read_b64_tr_b16 v[114:115], v209 offset:31232
	v_mfma_f32_32x32x16_bf16 v[80:95], v[184:187], v[160:163], v[80:95]
	v_add_f32_e32 v144, v118, v144
	v_add_f32_e32 v144, v119, v144
	v_add_f32_e32 v144, v120, v144
	v_add_f32_e32 v144, v121, v144
	v_cvt_pk_bf16_f32 v150, v116, v117
	v_cvt_pk_bf16_f32 v151, v118, v119
	ds_read_b64_tr_b16 v[116:117], v209 offset:27648
	ds_read_b64_tr_b16 v[118:119], v209 offset:28160
	v_mfma_f32_32x32x16_bf16 v[96:111], v[180:183], v[152:155], v[96:111]
	v_add_f32_e32 v144, v122, v144
	v_add_f32_e32 v144, v123, v144
	v_add_f32_e32 v144, v124, v144
	v_add_f32_e32 v180, v125, v144
	v_cvt_pk_bf16_f32 v144, v120, v121
	v_cvt_pk_bf16_f32 v145, v122, v123
	ds_read_b64_tr_b16 v[120:121], v209 offset:31744
	ds_read_b64_tr_b16 v[122:123], v209 offset:32256
	v_mfma_f32_32x32x16_bf16 v[80:95], v[176:179], v[152:155], v[80:95]
	v_add_f32_e32 v146, v126, v180
	v_add_f32_e32 v176, v127, v146
	v_cvt_pk_bf16_f32 v146, v124, v125
	v_cvt_pk_bf16_f32 v147, v126, v127
	s_add_i32 m0, s22, s63
	s_add_u32 s14, s32, 0x20000
	s_addc_u32 s15, s70, 0
	global_load_lds_dwordx4 v212, s[14:15]
	s_lshl_b32 s20, s66, 1
	s_add_i32 s20, s20, s64
	s_add_u32 s14, s98, 0x20000
	s_addc_u32 s15, s99, 0
	s_mov_b32 m0, s20
	s_add_i32 s20, s20, 0x1f80
	global_load_lds_dwordx4 v226, s[14:15]
	s_mov_b32 m0, s20
	s_nop 0
	global_load_lds_dwordx4 v226, s[14:15] offset:128
	s_waitcnt lgkmcnt(12)
	v_mfma_f32_32x32x16_bf16 v[32:47], v[164:167], v[188:191], v[32:47]
	v_max_f32_e32 v224, v96, v97
	v_max3_f32 v225, v98, v99, v81
	v_max3_f32 v224, v224, v80, v82
	v_max3_f32 v224, v224, v83, v100
	ds_read_b64_tr_b16 v[124:125], v209 offset:32768
	ds_read_b64_tr_b16 v[126:127], v209 offset:33280
	v_mfma_f32_32x32x16_bf16 v[48:63], v[164:167], v[128:131], v[48:63]
	v_max3_f32 v225, v225, v102, v103
	v_max3_f32 v224, v224, v101, v84
	v_max3_f32 v225, v225, v86, v87
	v_max3_f32 v224, v224, v85, v104
	ds_read_b64_tr_b16 v[128:129], v209 offset:36864
	ds_read_b64_tr_b16 v[130:131], v209 offset:37376
	s_waitcnt lgkmcnt(12)
	v_mfma_f32_32x32x16_bf16 v[32:47], v[156:159], v[132:135], v[32:47]
	v_max3_f32 v225, v225, v106, v107
	v_max3_f32 v224, v224, v105, v88
	v_max3_f32 v225, v225, v90, v91
	v_max3_f32 v224, v224, v89, v108
	ds_read_b64_tr_b16 v[132:133], v209 offset:33792
	ds_read_b64_tr_b16 v[134:135], v209 offset:34304
	v_mfma_f32_32x32x16_bf16 v[48:63], v[156:159], v[136:139], v[48:63]
	v_max3_f32 v225, v225, v110, v111
	v_max3_f32 v224, v224, v109, v92
	v_max3_f32 v225, v225, v94, v95
	v_max3_f32 v224, v224, v93, v225
	ds_read_b64_tr_b16 v[136:137], v209 offset:37888
	ds_read_b64_tr_b16 v[138:139], v209 offset:38400
	s_waitcnt lgkmcnt(12)
	v_mfma_f32_32x32x16_bf16 v[32:47], v[148:151], v[140:143], v[32:47]
	v_mov_b32_e32 v225, v224
	v_add_f32_e32 v249, v215, v176
	s_nop 0
	v_permlane32_swap_b32_e32 v224, v225
	v_max_f32_e32 v224, v224, v225
	v_cmp_lt_f32_e32 vcc, s33, v224
	s_nop 0
	s_mov_b64 s[20:21], vcc
	s_cbranch_vccnz .LBB0_321
.LBB0_314:
	v_exp_f32_e32 v96, v96
	v_exp_f32_e32 v97, v97
	ds_read_b64_tr_b16 v[140:141], v209 offset:34816
	ds_read_b64_tr_b16 v[142:143], v209 offset:35328
	v_mfma_f32_32x32x16_bf16 v[48:63], v[148:151], v[112:115], v[48:63]
	v_exp_f32_e32 v98, v98
	v_exp_f32_e32 v99, v99
	v_exp_f32_e32 v100, v100
	ds_read_b64_tr_b16 v[112:113], v209 offset:38912
	ds_read_b64_tr_b16 v[114:115], v209 offset:39424
	s_waitcnt lgkmcnt(12)
	v_mfma_f32_32x32x16_bf16 v[32:47], v[144:147], v[116:119], v[32:47]
	v_exp_f32_e32 v101, v101
	v_exp_f32_e32 v102, v102
	v_exp_f32_e32 v103, v103
	ds_read_b64_tr_b16 v[116:117], v209 offset:35840
	ds_read_b64_tr_b16 v[118:119], v209 offset:36352
	v_mfma_f32_32x32x16_bf16 v[48:63], v[144:147], v[120:123], v[48:63]
	v_exp_f32_e32 v104, v104
	v_exp_f32_e32 v105, v105
	v_exp_f32_e32 v106, v106
	ds_read_b64_tr_b16 v[120:121], v209 offset:39936
	ds_read_b64_tr_b16 v[122:123], v209 offset:40448
	s_waitcnt lgkmcnt(12)
	v_mfma_f32_32x32x16_bf16 v[16:31], v[164:167], v[124:127], v[16:31]
	v_exp_f32_e32 v107, v107
	v_exp_f32_e32 v108, v108
	v_exp_f32_e32 v109, v109
	v_add_u32_e32 v124, s66, v247
	ds_read_b128 v[204:207], v124
	ds_read_b128 v[200:203], v124 offset:512
	v_mfma_f32_32x32x16_bf16 v[0:15], v[164:167], v[128:131], v[0:15]
	v_exp_f32_e32 v110, v110
	v_exp_f32_e32 v111, v111
	v_exp_f32_e32 v80, v80
	ds_read_b128 v[196:199], v124 offset:2048
	ds_read_b128 v[192:195], v124 offset:2560
	s_waitcnt lgkmcnt(12)
	v_mfma_f32_32x32x16_bf16 v[16:31], v[156:159], v[132:135], v[16:31]
	v_exp_f32_e32 v81, v81
	v_exp_f32_e32 v82, v82
	v_exp_f32_e32 v83, v83
	ds_read_b128 v[188:191], v124 offset:4096
	ds_read_b128 v[184:187], v124 offset:4608
	v_mfma_f32_32x32x16_bf16 v[0:15], v[156:159], v[136:139], v[0:15]
	v_exp_f32_e32 v84, v84
	v_exp_f32_e32 v85, v85
	v_exp_f32_e32 v86, v86
	ds_read_b128 v[180:183], v124 offset:6144
	ds_read_b128 v[176:179], v124 offset:6656
	s_waitcnt lgkmcnt(12)
	v_mfma_f32_32x32x16_bf16 v[16:31], v[148:151], v[140:143], v[16:31]
	v_exp_f32_e32 v87, v87
	v_exp_f32_e32 v88, v88
	v_exp_f32_e32 v89, v89
	v_mfma_f32_32x32x16_bf16 v[0:15], v[148:151], v[112:115], v[0:15]
	v_exp_f32_e32 v90, v90
	v_exp_f32_e32 v91, v91
	s_waitcnt lgkmcnt(8)
	v_mfma_f32_32x32x16_bf16 v[16:31], v[144:147], v[116:119], v[16:31]
	v_exp_f32_e32 v92, v92
	v_exp_f32_e32 v93, v93
	v_mfma_f32_32x32x16_bf16 v[0:15], v[144:147], v[120:123], v[0:15]
	v_exp_f32_e32 v94, v94
	v_exp_f32_e32 v95, v95
	s_waitcnt vmcnt(3) lgkmcnt(0)
	s_barrier
	s_cmp_eq_u64 s[20:21], 0
	s_cbranch_scc1 .LBB0_316
	s_waitcnt lgkmcnt(0)
	v_add_u32_e32 v208, s65, v248
	ds_read_b128 v[112:115], v208 offset:96
	ds_read_b128 v[116:119], v208 offset:64
	ds_read_b128 v[120:123], v208 offset:32
	ds_read_b128 v[124:127], v208
	s_waitcnt lgkmcnt(3)
	v_pk_mul_f32 v[44:45], v[44:45], v[112:113]
	s_waitcnt lgkmcnt(2)
	v_pk_mul_f32 v[40:41], v[40:41], v[116:117]
	s_waitcnt lgkmcnt(1)
	v_pk_mul_f32 v[36:37], v[36:37], v[120:121]
	v_pk_mul_f32 v[46:47], v[46:47], v[114:115]
	v_pk_mul_f32 v[42:43], v[42:43], v[118:119]
	v_pk_mul_f32 v[38:39], v[38:39], v[122:123]
	s_waitcnt lgkmcnt(0)
	v_pk_mul_f32 v[34:35], v[34:35], v[126:127]
	v_pk_mul_f32 v[32:33], v[32:33], v[124:125]
	v_pk_mul_f32 v[60:61], v[60:61], v[112:113]
	v_pk_mul_f32 v[56:57], v[56:57], v[116:117]
	v_pk_mul_f32 v[52:53], v[52:53], v[120:121]
	v_pk_mul_f32 v[62:63], v[62:63], v[114:115]
	v_pk_mul_f32 v[58:59], v[58:59], v[118:119]
	v_pk_mul_f32 v[54:55], v[54:55], v[122:123]
	v_pk_mul_f32 v[50:51], v[50:51], v[126:127]
	v_pk_mul_f32 v[48:49], v[48:49], v[124:125]
	v_pk_mul_f32 v[28:29], v[28:29], v[112:113]
	v_pk_mul_f32 v[24:25], v[24:25], v[116:117]
	v_pk_mul_f32 v[20:21], v[20:21], v[120:121]
	v_pk_mul_f32 v[30:31], v[30:31], v[114:115]
	v_pk_mul_f32 v[26:27], v[26:27], v[118:119]
	v_pk_mul_f32 v[22:23], v[22:23], v[122:123]
	v_pk_mul_f32 v[18:19], v[18:19], v[126:127]
	v_pk_mul_f32 v[16:17], v[16:17], v[124:125]
	v_pk_mul_f32 v[12:13], v[12:13], v[112:113]
	v_pk_mul_f32 v[8:9], v[8:9], v[116:117]
	v_pk_mul_f32 v[4:5], v[4:5], v[120:121]
	v_pk_mul_f32 v[14:15], v[14:15], v[114:115]
	v_pk_mul_f32 v[10:11], v[10:11], v[118:119]
	v_pk_mul_f32 v[6:7], v[6:7], v[122:123]
	v_pk_mul_f32 v[2:3], v[2:3], v[126:127]
	v_pk_mul_f32 v[0:1], v[0:1], v[124:125]

.LBB0_318:
	v_max_f32_e32 v64, v222, v222
	v_max_f32_e32 v222, 0, v64
	v_exp_f32_e64 v223, -v222
	v_add_f32_e32 v246, v246, v222
	v_xor_b32_e32 v64, 0x80000000, v246
	v_mov_b32_e32 v65, v64
	v_mov_b32_e32 v66, v64
	v_mov_b32_e32 v67, v64
	v_mov_b32_e32 v68, v64
	v_mov_b32_e32 v69, v64
	v_mov_b32_e32 v70, v64
	v_mov_b32_e32 v71, v64
	v_mov_b32_e32 v72, v64
	v_mov_b32_e32 v73, v64
	v_mov_b32_e32 v74, v64
	v_mov_b32_e32 v75, v64
	v_mov_b32_e32 v76, v64
	v_mov_b32_e32 v77, v64
	v_mov_b32_e32 v78, v64
	v_mov_b32_e32 v79, v64
	s_and_saveexec_b64 s[14:15], s[2:3]
	ds_write_b32 v243, v223
	s_or_b64 exec, exec, s[14:15]
	v_sub_f32_e32 v143, v143, v222
	v_sub_f32_e32 v142, v142, v222
	v_sub_f32_e32 v141, v141, v222
	v_sub_f32_e32 v140, v140, v222
	v_sub_f32_e32 v139, v139, v222
	v_sub_f32_e32 v138, v138, v222
	v_sub_f32_e32 v137, v137, v222
	v_sub_f32_e32 v136, v136, v222
	v_sub_f32_e32 v135, v135, v222
	v_sub_f32_e32 v134, v134, v222
	v_sub_f32_e32 v133, v133, v222
	v_sub_f32_e32 v132, v132, v222
	v_sub_f32_e32 v131, v131, v222
	v_sub_f32_e32 v130, v130, v222
	v_sub_f32_e32 v129, v129, v222
	v_sub_f32_e32 v128, v128, v222
	v_sub_f32_e32 v127, v127, v222
	v_sub_f32_e32 v126, v126, v222
	v_sub_f32_e32 v125, v125, v222
	v_sub_f32_e32 v124, v124, v222
	v_sub_f32_e32 v123, v123, v222
	v_sub_f32_e32 v122, v122, v222
	v_sub_f32_e32 v121, v121, v222
	v_sub_f32_e32 v120, v120, v222
	v_sub_f32_e32 v119, v119, v222
	v_sub_f32_e32 v118, v118, v222
	v_sub_f32_e32 v117, v117, v222
	v_sub_f32_e32 v116, v116, v222
	v_sub_f32_e32 v115, v115, v222
	v_sub_f32_e32 v114, v114, v222
	v_sub_f32_e32 v113, v113, v222
	v_sub_f32_e32 v112, v112, v222
	v_mul_f32_e32 v215, v215, v223
	s_waitcnt lgkmcnt(0)
	s_branch .LBB0_311
.LBB0_321:
	v_max_f32_e32 v64, v224, v224
	v_max_f32_e32 v224, 0, v64
	v_exp_f32_e64 v225, -v224
	v_add_f32_e32 v246, v246, v224
	v_xor_b32_e32 v64, 0x80000000, v246
	v_mov_b32_e32 v65, v64
	v_mov_b32_e32 v66, v64
	v_mov_b32_e32 v67, v64
	v_mov_b32_e32 v68, v64
	v_mov_b32_e32 v69, v64
	v_mov_b32_e32 v70, v64
	v_mov_b32_e32 v71, v64
	v_mov_b32_e32 v72, v64
	v_mov_b32_e32 v73, v64
	v_mov_b32_e32 v74, v64
	v_mov_b32_e32 v75, v64
	v_mov_b32_e32 v76, v64
	v_mov_b32_e32 v77, v64
	v_mov_b32_e32 v78, v64
	v_mov_b32_e32 v79, v64
	s_and_saveexec_b64 s[14:15], s[2:3]
	ds_write_b32 v243, v225
	s_or_b64 exec, exec, s[14:15]
	v_sub_f32_e32 v111, v111, v224
	v_sub_f32_e32 v110, v110, v224
	v_sub_f32_e32 v109, v109, v224
	v_sub_f32_e32 v108, v108, v224
	v_sub_f32_e32 v107, v107, v224
	v_sub_f32_e32 v106, v106, v224
	v_sub_f32_e32 v105, v105, v224
	v_sub_f32_e32 v104, v104, v224
	v_sub_f32_e32 v103, v103, v224
	v_sub_f32_e32 v102, v102, v224
	v_sub_f32_e32 v101, v101, v224
	v_sub_f32_e32 v100, v100, v224
	v_sub_f32_e32 v99, v99, v224
	v_sub_f32_e32 v98, v98, v224
	v_sub_f32_e32 v97, v97, v224
	v_sub_f32_e32 v96, v96, v224
	v_sub_f32_e32 v95, v95, v224
	v_sub_f32_e32 v94, v94, v224
	v_sub_f32_e32 v93, v93, v224
	v_sub_f32_e32 v92, v92, v224
	v_sub_f32_e32 v91, v91, v224
	v_sub_f32_e32 v90, v90, v224
	v_sub_f32_e32 v89, v89, v224
	v_sub_f32_e32 v88, v88, v224
	v_sub_f32_e32 v87, v87, v224
	v_sub_f32_e32 v86, v86, v224
	v_sub_f32_e32 v85, v85, v224
	v_sub_f32_e32 v84, v84, v224
	v_sub_f32_e32 v83, v83, v224
	v_sub_f32_e32 v82, v82, v224
	v_sub_f32_e32 v81, v81, v224
	v_sub_f32_e32 v80, v80, v224
	v_mul_f32_e32 v249, v249, v225
	s_waitcnt lgkmcnt(0)
	s_branch .LBB0_314
